# attention: QK accumulator-init block kept persistent in 16 spare VGPRs and rebuilt only when bias-minus-max changes
# baseline (speedup 1.0000x reference)
; __device__ __forceinline__ void attn_item(CP& P, int L, int sq, int hh, int qt, float lam, float lam_init, LAS unsigned char* lds) {
;     ...
;     for (int t = 0; t < ntiles; ++t) {
;         { const int tn = (t + 2 < ntiles) ? t + 2 : ntiles - 1; ATT_DMA(tn, (t + 2) & 3); }
;         const int k0_ = t * 64; const bool farR_ = (k0_ - (q0w + 31) >= 128), farL_ = (q0w - (k0_ + 63) >= 128); far_ = farR_ || farL_;
;         const float cinit_ = (far_ ? (farR_ ? tbl[256] : tbl[0]) : 0.f) - mref;
.LBB0_65:
	s_nop 8
	v_max_f32_e32 v4, v17, v17
	v_max_f32_e32 v5, v33, v33
	v_max_f32_e32 v4, v5, v4
	v_max_f32_e32 v5, v18, v18
	v_max_f32_e32 v6, v34, v34
	v_max_f32_e32 v5, v6, v5
	v_max_f32_e32 v6, v19, v19
	v_max_f32_e32 v7, v35, v35
	v_max3_f32 v4, v32, v16, v4
	v_max_f32_e32 v6, v7, v6
	v_max3_f32 v4, v4, v5, v6
	v_max_f32_e32 v5, v20, v20
	v_max_f32_e32 v6, v36, v36
	v_max_f32_e32 v5, v6, v5
	v_max_f32_e32 v6, v21, v21
	v_max_f32_e32 v7, v37, v37
	v_max_f32_e32 v6, v7, v6
	v_max3_f32 v4, v4, v5, v6
	v_max_f32_e32 v5, v22, v22
	v_max_f32_e32 v6, v38, v38
	v_max_f32_e32 v5, v6, v5
	v_max_f32_e32 v6, v23, v23
	v_max_f32_e32 v7, v39, v39
	v_max_f32_e32 v6, v7, v6
	v_max3_f32 v4, v4, v5, v6
	v_max_f32_e32 v5, v24, v24
	v_max_f32_e32 v6, v40, v40
	v_max_f32_e32 v5, v6, v5
	v_max_f32_e32 v6, v25, v25
	v_max_f32_e32 v7, v41, v41
	v_max_f32_e32 v6, v7, v6
	v_max3_f32 v4, v4, v5, v6
	v_max_f32_e32 v5, v26, v26
	v_max_f32_e32 v6, v42, v42
	v_max_f32_e32 v5, v6, v5
	v_max_f32_e32 v6, v27, v27
	v_max_f32_e32 v7, v43, v43
	v_max_f32_e32 v6, v7, v6
	v_max3_f32 v4, v4, v5, v6
	v_max_f32_e32 v5, v28, v28
	v_max_f32_e32 v6, v44, v44
	v_max_f32_e32 v5, v6, v5
	v_max_f32_e32 v6, v29, v29
	v_max_f32_e32 v7, v45, v45
	v_max_f32_e32 v6, v7, v6
	v_max3_f32 v4, v4, v5, v6
	v_max_f32_e32 v5, v30, v30
	v_max_f32_e32 v6, v46, v46
	v_max_f32_e32 v5, v6, v5
	v_max_f32_e32 v6, v31, v31
	v_max_f32_e32 v7, v47, v47
	v_max_f32_e32 v6, v7, v6
	v_max3_f32 v4, v4, v5, v6
	v_and_b32_e32 v6, 64, v227
	v_xor_b32_e32 v5, 32, v227
	v_add_u32_e32 v6, 64, v6
	v_cmp_lt_i32_e32 vcc, v5, v6
	v_bfe_u32 v1, v48, 2, 2
	v_lshlrev_b32_e32 v0, 3, v48
	v_cndmask_b32_e32 v5, v227, v5, vcc
	v_lshlrev_b32_e32 v129, 2, v5
	ds_bpermute_b32 v5, v129, v4
	v_or_b32_e32 v2, v127, v1
	v_lshlrev_b32_e32 v3, 1, v48
	v_lshlrev_b32_e32 v2, 8, v2
	v_and_b32_e32 v3, 32, v3
	v_and_b32_e32 v0, 24, v0
	v_or3_b32 v138, v0, v3, v2
	s_waitcnt lgkmcnt(0)
	v_max_f32_e32 v0, v5, v5
	v_max_f32_e32 v48, v4, v0
	v_sub_f32_e32 v32, v32, v48
	v_sub_f32_e32 v16, v16, v48
	v_exp_f32_e32 v50, v32
	v_exp_f32_e32 v51, v16
	v_sub_f32_e32 v16, v33, v48
	v_sub_f32_e32 v17, v17, v48
	v_exp_f32_e32 v16, v16
	v_exp_f32_e32 v17, v17
	v_sub_f32_e32 v32, v34, v48
	v_sub_f32_e32 v18, v18, v48
	v_exp_f32_e32 v32, v32
	v_exp_f32_e32 v33, v18
	v_sub_f32_e32 v18, v35, v48
	v_sub_f32_e32 v19, v19, v48
	v_exp_f32_e32 v18, v18
	v_exp_f32_e32 v19, v19
	v_sub_f32_e32 v36, v36, v48
	v_sub_f32_e32 v20, v20, v48
	v_pk_add_f32 v[34:35], v[50:51], 0 op_sel_hi:[1,0]
	v_exp_f32_e32 v52, v36
	v_exp_f32_e32 v53, v20
	v_sub_f32_e32 v20, v37, v48
	v_sub_f32_e32 v21, v21, v48
	v_pk_add_f32 v[34:35], v[16:17], v[34:35]
	v_exp_f32_e32 v20, v20
	v_exp_f32_e32 v21, v21
	v_sub_f32_e32 v36, v38, v48
	v_sub_f32_e32 v22, v22, v48
	v_pk_add_f32 v[34:35], v[32:33], v[34:35]
	v_exp_f32_e32 v36, v36
	v_exp_f32_e32 v37, v22
	v_sub_f32_e32 v22, v39, v48
	v_sub_f32_e32 v23, v23, v48
	v_pk_add_f32 v[34:35], v[18:19], v[34:35]
	v_exp_f32_e32 v22, v22
	v_exp_f32_e32 v23, v23
	v_sub_f32_e32 v38, v40, v48
	v_sub_f32_e32 v24, v24, v48
	v_pk_add_f32 v[34:35], v[52:53], v[34:35]
	v_exp_f32_e32 v38, v38
	v_exp_f32_e32 v39, v24
	v_sub_f32_e32 v24, v41, v48
	v_sub_f32_e32 v25, v25, v48
	v_pk_add_f32 v[34:35], v[20:21], v[34:35]
	v_exp_f32_e32 v24, v24
	v_exp_f32_e32 v25, v25
	v_sub_f32_e32 v40, v42, v48
	v_sub_f32_e32 v26, v26, v48
	v_pk_add_f32 v[34:35], v[36:37], v[34:35]
	v_exp_f32_e32 v40, v40
	v_exp_f32_e32 v41, v26
	v_sub_f32_e32 v26, v43, v48
	v_sub_f32_e32 v27, v27, v48
	v_pk_add_f32 v[34:35], v[22:23], v[34:35]
	v_exp_f32_e32 v26, v26
	v_exp_f32_e32 v27, v27
	v_sub_f32_e32 v42, v44, v48
	v_sub_f32_e32 v28, v28, v48
	v_pk_add_f32 v[34:35], v[38:39], v[34:35]
	v_exp_f32_e32 v42, v42
	v_exp_f32_e32 v43, v28
	v_sub_f32_e32 v28, v45, v48
	v_sub_f32_e32 v29, v29, v48
	v_pk_add_f32 v[34:35], v[24:25], v[34:35]
	v_exp_f32_e32 v28, v28
	v_exp_f32_e32 v29, v29
	v_sub_f32_e32 v44, v46, v48
	v_sub_f32_e32 v30, v30, v48
	v_pk_add_f32 v[34:35], v[40:41], v[34:35]
	v_exp_f32_e32 v44, v44
	v_exp_f32_e32 v45, v30
	v_sub_f32_e32 v30, v47, v48
	v_sub_f32_e32 v31, v31, v48
	v_pk_add_f32 v[34:35], v[26:27], v[34:35]
	v_exp_f32_e32 v30, v30
	v_exp_f32_e32 v31, v31
	v_exp_f32_e64 v0, -v48
	v_pk_add_f32 v[34:35], v[42:43], v[34:35]
	s_lshl_b32 s2, s14, 7
	v_pk_add_f32 v[34:35], v[28:29], v[34:35]
	v_mul_f32_e32 v0, 0, v0
	v_pk_add_f32 v[34:35], v[44:45], v[34:35]
	v_cvt_pk_bf16_f32 v220, v50, v16
	v_pk_add_f32 v[34:35], v[30:31], v[34:35]
	v_sub_u32_e32 v16, v127, v128
	v_pk_add_f32 v[34:35], v[34:35], v[34:35] op_sel_hi:[0,1]
	s_and_b64 s[0:1], s[0:1], exec
	v_mov_b32_e32 v14, v0
	v_mov_b32_e32 v15, v0
	s_waitcnt vmcnt(4) lgkmcnt(0)
	s_barrier
	v_mov_b32_e32 v49, v0
	v_mov_b32_e32 v34, v193
	v_subrev_u32_e32 v16, s10, v16
	s_cselect_b32 s15, 32, 64
	v_lshlrev_b32_e32 v139, 6, v1
	v_mov_b32_e32 v1, v0
	v_mov_b32_e32 v2, v0
	v_mov_b32_e32 v3, v0
	v_mov_b32_e32 v4, v0
	v_mov_b32_e32 v5, v0
	v_mov_b32_e32 v6, v0
	v_mov_b32_e32 v7, v0
	v_mov_b32_e32 v8, v0
	v_mov_b32_e32 v9, v0
	v_mov_b32_e32 v10, v0
	v_mov_b32_e32 v11, v0
	v_mov_b32_e32 v12, v0
	v_mov_b32_e32 v13, v0
	v_pk_add_f32 v[124:125], v[48:49], v[34:35]
	v_cvt_pk_bf16_f32 v208, v39, v25
	v_cvt_pk_bf16_f32 v209, v41, v27
	v_cvt_pk_bf16_f32 v210, v43, v29
	v_cvt_pk_bf16_f32 v211, v45, v31
	v_cvt_pk_bf16_f32 v212, v51, v17
	v_cvt_pk_bf16_f32 v213, v33, v19
	v_cvt_pk_bf16_f32 v214, v53, v21
	v_cvt_pk_bf16_f32 v215, v37, v23
	v_cvt_pk_bf16_f32 v216, v38, v24
	v_cvt_pk_bf16_f32 v217, v40, v26
	v_cvt_pk_bf16_f32 v218, v42, v28
	v_cvt_pk_bf16_f32 v219, v44, v30
	v_cvt_pk_bf16_f32 v221, v32, v18
	v_cvt_pk_bf16_f32 v222, v52, v20
	v_cvt_pk_bf16_f32 v223, v36, v22
	v_subrev_u32_e32 v141, s20, v16
	v_mov_b64_e32 v[62:63], v[14:15]
	v_mov_b64_e32 v[46:47], v[14:15]
	v_mov_b64_e32 v[30:31], v[14:15]
	v_ashrrev_i32_e32 v115, 31, v114
	s_mov_b32 s14, 64
	s_mov_b32 s16, 1
	s_add_i32 s17, s15, -1
	v_add_u32_e32 v140, 0, v138
	v_xor_b32_e32 v137, 64, v139
	v_xor_b32_e32 v136, 0x80, v139
	v_xor_b32_e32 v135, 0xc0, v139
	s_add_i32 s18, s19, 0x9e
	s_addk_i32 s19, 0xff42
	s_mov_b32 s20, 0x20000
	v_mov_b64_e32 v[60:61], v[12:13]
	v_mov_b64_e32 v[58:59], v[10:11]
	v_mov_b64_e32 v[56:57], v[8:9]
	v_mov_b64_e32 v[54:55], v[6:7]
	v_mov_b64_e32 v[52:53], v[4:5]
	v_mov_b64_e32 v[50:51], v[2:3]
	v_mov_b64_e32 v[48:49], v[0:1]
	v_mov_b64_e32 v[44:45], v[12:13]
	v_mov_b64_e32 v[42:43], v[10:11]
	v_mov_b64_e32 v[40:41], v[8:9]
	v_mov_b64_e32 v[38:39], v[6:7]
	v_mov_b64_e32 v[36:37], v[4:5]
	v_mov_b64_e32 v[34:35], v[2:3]
	v_mov_b64_e32 v[32:33], v[0:1]
	v_mov_b64_e32 v[28:29], v[12:13]
	v_mov_b64_e32 v[26:27], v[10:11]
	v_mov_b64_e32 v[24:25], v[8:9]
	v_mov_b64_e32 v[22:23], v[6:7]
	v_mov_b64_e32 v[20:21], v[4:5]
	v_mov_b64_e32 v[18:19], v[2:3]
	v_mov_b64_e32 v[16:17], v[0:1]
	v_mov_b32_e32 v190, 0x7fc00000
	s_branch .LBB0_67

; #define SB() __builtin_amdgcn_sched_barrier(0)
; #define ATT_QKM(t) do { _Pragma("unroll") for (int kb = 0; kb < 2; ++kb) _Pragma("unroll") for (int i = 0; i < 16; ++i) p[kb][i] = cinit_; \
;         SB(); __builtin_amdgcn_s_setprio(1); \
;         _Pragma("unroll") for (int s_ = 0; s_ < 4; ++s_) _Pragma("unroll") for (int kb = 0; kb < 2; ++kb) p[kb] = MFMA32(kf[kb * 4 + s_], qf[s_], p[kb]); \
;         __builtin_amdgcn_s_setprio(0); SB(); } while (0)
; #define ATT_LWAIT() asm volatile("s_waitcnt lgkmcnt(0)" ::: "memory")
; #define ATT_VRD(dst, c) do { const unsigned va_ = vaddr_ + 64u * (unsigned)((c) ^ vq); \
;         ATT_TR(dst[0], va_, 0);     ATT_TR(dst[1], va_, 2048);  ATT_TR(dst[2], va_, 4096);  ATT_TR(dst[3], va_, 6144); \
;         ATT_TR(dst[4], va_, 8192);  ATT_TR(dst[5], va_, 10240); ATT_TR(dst[6], va_, 12288); ATT_TR(dst[7], va_, 14336); } while (0)
; __device__ __forceinline__ void attn_item(CP& P, int L, int sq, int hh, int qt, float lam, float lam_init, LAS unsigned char* lds) {
;     ...
;         const int k0_ = t * 64; const bool farR_ = (k0_ - (q0w + 31) >= 128), farL_ = (q0w - (k0_ + 63) >= 128); far_ = farR_ || farL_;
;         const float cinit_ = (far_ ? (farR_ ? tbl[256] : tbl[0]) : 0.f) - mref;
;         if (t > 0) {
;             const unsigned vaddr_ = (unsigned)(size_t)(lds + ((t - 1) & 3) * A_SLOT + vfo); s16x4 va0_[8], va1_[8];
;             ATT_VRD(va0_, 0); ATT_VRD(va1_, 1); ATT_LWAIT(); SB();
;             ATT_VMM2(va0_, 0, va1_, 1); SB();
;             ATT_VRD(va0_, 2); ATT_VRD(va1_, 3); ATT_LWAIT(); ATT_KRD(t & 3); SB();
;             ATT_VMM2(va0_, 2, va1_, 3); SB(); ATT_LWAIT(); SB();
;         } else { ATT_KRD(0); ATT_LWAIT(); SB(); }
;         ATT_QKM(t);
.LBB0_72:
	s_and_b32 s5, s20, 0x18000
	s_add_i32 s4, s20, 0xfffe8000
	s_and_b32 s4, s4, 0x18000
	v_add_u32_e32 v65, s4, v134
	v_add_u32_e32 v94, v130, v65
	ds_read_b128 v[162:165], v94
	ds_read_b128 v[166:169], v94 offset:4096
	v_add_u32_e32 v94, v131, v65
	ds_read_b128 v[170:173], v94
	ds_read_b128 v[174:177], v94 offset:4096
	v_add_u32_e32 v94, v132, v65
	ds_read_b128 v[178:181], v94
	ds_read_b128 v[182:185], v94 offset:4096
	v_add_u32_e32 v65, v133, v65
	ds_read_b128 v[186:189], v65
	ds_read_b128 v[200:203], v65 offset:4096
	s_waitcnt lgkmcnt(0)
	v_sub_f32_e32 v64, v64, v124
	v_cmp_neq_f32_e32 vcc, v64, v190
	s_cbranch_vccz .Lc0_ok
	v_mov_b32_e32 v146, v64
	v_mov_b32_e32 v147, v64
	v_mov_b32_e32 v148, v64
	v_mov_b32_e32 v149, v64
	v_mov_b32_e32 v150, v64
	v_mov_b32_e32 v151, v64
	v_mov_b32_e32 v152, v64
	v_mov_b32_e32 v153, v64
	v_mov_b32_e32 v154, v64
	v_mov_b32_e32 v155, v64
	v_mov_b32_e32 v156, v64
	v_mov_b32_e32 v157, v64
	v_mov_b32_e32 v158, v64
	v_mov_b32_e32 v159, v64
	v_mov_b32_e32 v160, v64
	v_mov_b32_e32 v161, v64
	v_mov_b32_e32 v190, v64
.Lc0_ok:
	s_setprio 1
	s_nop 0
	v_mfma_f32_32x32x16_bf16 v[80:95], v[162:165], v[96:99], v[146:161]
	v_mfma_f32_32x32x16_bf16 v[64:79], v[166:169], v[96:99], v[146:161]
	v_mfma_f32_32x32x16_bf16 v[80:95], v[170:173], v[100:103], v[80:95]
	v_mfma_f32_32x32x16_bf16 v[64:79], v[174:177], v[100:103], v[64:79]
	v_mfma_f32_32x32x16_bf16 v[80:95], v[178:181], v[104:107], v[80:95]
	v_mfma_f32_32x32x16_bf16 v[64:79], v[182:185], v[104:107], v[64:79]
	v_mfma_f32_32x32x16_bf16 v[80:95], v[186:189], v[108:111], v[80:95]
	v_mfma_f32_32x32x16_bf16 v[64:79], v[200:203], v[108:111], v[64:79]
	s_setprio 0
	v_add_u32_e32 v224, s5, v140
	v_add_u32_e32 v224, 0x4000, v224
	v_add_u32_e32 v225, v139, v224
	ds_read_b64_tr_b16 v[162:163], v225 offset:0
	ds_read_b64_tr_b16 v[164:165], v225 offset:2048
	ds_read_b64_tr_b16 v[166:167], v225 offset:4096
	ds_read_b64_tr_b16 v[168:169], v225 offset:6144
	ds_read_b64_tr_b16 v[170:171], v225 offset:8192
	ds_read_b64_tr_b16 v[172:173], v225 offset:10240
	ds_read_b64_tr_b16 v[174:175], v225 offset:12288
	ds_read_b64_tr_b16 v[176:177], v225 offset:14336
	v_add_u32_e32 v225, v137, v224
	ds_read_b64_tr_b16 v[178:179], v225 offset:0
	ds_read_b64_tr_b16 v[180:181], v225 offset:2048
	ds_read_b64_tr_b16 v[182:183], v225 offset:4096
	ds_read_b64_tr_b16 v[184:185], v225 offset:6144
	ds_read_b64_tr_b16 v[186:187], v225 offset:8192
	ds_read_b64_tr_b16 v[188:189], v225 offset:10240
	ds_read_b64_tr_b16 v[200:201], v225 offset:12288
	ds_read_b64_tr_b16 v[202:203], v225 offset:14336
	s_waitcnt lgkmcnt(0)
	s_andn2_b64 vcc, exec, s[0:1]
	s_cbranch_vccnz .LBB0_74
	v_add_u32_e32 v158, s14, v141
	v_mov_b32_e32 v142, 0x80
	s_movk_i32 s0, 0xff80
	v_med3_i32 v142, v158, s0, v142
	s_add_i32 s0, 0, 0x20000
	v_lshl_add_u32 v150, v142, 2, s0
	v_mov_b32_e32 v142, 0x7f
	s_movk_i32 s1, 0xff7f
	v_med3_i32 v142, v158, s1, v142
	v_lshl_add_u32 v151, v142, 2, s0
	v_mov_b32_e32 v142, 0x7e
	s_movk_i32 s1, 0xff7e
	v_med3_i32 v142, v158, s1, v142
	v_lshl_add_u32 v152, v142, 2, s0
	v_mov_b32_e32 v142, 0x7d
	s_movk_i32 s1, 0xff7d
	v_med3_i32 v142, v158, s1, v142
	v_lshl_add_u32 v153, v142, 2, s0
	v_mov_b32_e32 v142, 0x78
	s_movk_i32 s1, 0xff78
	v_med3_i32 v142, v158, s1, v142
	v_lshl_add_u32 v154, v142, 2, s0
	v_mov_b32_e32 v142, 0x77
	s_movk_i32 s1, 0xff77
	v_med3_i32 v142, v158, s1, v142
	v_lshl_add_u32 v155, v142, 2, s0
	v_mov_b32_e32 v142, 0x76
	s_movk_i32 s1, 0xff76
	v_med3_i32 v142, v158, s1, v142
	v_lshl_add_u32 v156, v142, 2, s0
	v_mov_b32_e32 v142, 0x75
	s_movk_i32 s1, 0xff75
	v_med3_i32 v142, v158, s1, v142
	v_lshl_add_u32 v157, v142, 2, s0
	v_mov_b32_e32 v142, 0x70
	s_movk_i32 s1, 0xff70
	v_med3_i32 v142, v158, s1, v142
	v_mov_b32_e32 v143, 0x6f
	s_movk_i32 s1, 0xff6f
	v_med3_i32 v143, v158, s1, v143
	v_mov_b32_e32 v144, 0x6e
	s_movk_i32 s1, 0xff6e
	v_med3_i32 v144, v158, s1, v144
	v_mov_b32_e32 v145, 0x6d
	s_movk_i32 s1, 0xff6d
	v_med3_i32 v145, v158, s1, v145
	v_mov_b32_e32 v146, 0x68
	s_movk_i32 s1, 0xff68
	v_med3_i32 v146, v158, s1, v146
	v_mov_b32_e32 v147, 0x67
	s_movk_i32 s1, 0xff67
	v_med3_i32 v147, v158, s1, v147
	v_mov_b32_e32 v148, 0x66
	s_movk_i32 s1, 0xff66
	v_med3_i32 v148, v158, s1, v148
	v_mov_b32_e32 v149, 0x65
	s_movk_i32 s1, 0xff65
	v_med3_i32 v149, v158, s1, v149
	v_lshl_add_u32 v142, v142, 2, s0
	v_lshl_add_u32 v143, v143, 2, s0
	v_lshl_add_u32 v144, v144, 2, s0
	v_lshl_add_u32 v145, v145, 2, s0
	v_lshl_add_u32 v146, v146, 2, s0
	v_lshl_add_u32 v147, v147, 2, s0
	v_lshl_add_u32 v148, v148, 2, s0
	v_lshl_add_u32 v149, v149, 2, s0
	ds_read_b32 v142, v142 offset:576
	ds_read_b32 v143, v143 offset:580
	ds_read_b32 v144, v144 offset:584
	ds_read_b32 v145, v145 offset:588
	ds_read_b32 v146, v146 offset:608
	ds_read_b32 v147, v147 offset:612
	ds_read_b32 v148, v148 offset:616
	ds_read_b32 v149, v149 offset:620
	ds_read_b32 v150, v150 offset:512
	ds_read_b32 v151, v151 offset:516
	ds_read_b32 v152, v152 offset:520
	ds_read_b32 v153, v153 offset:524
	ds_read_b32 v154, v154 offset:544
	ds_read_b32 v155, v155 offset:548
	ds_read_b32 v156, v156 offset:552
	ds_read_b32 v157, v157 offset:556
	s_waitcnt lgkmcnt(0)
; #define SB() __builtin_amdgcn_sched_barrier(0)
; #define ATT_LWAIT() asm volatile("s_waitcnt lgkmcnt(0)" ::: "memory")
; #define ATT_VRD(dst, c) do { const unsigned va_ = vaddr_ + 64u * (unsigned)((c) ^ vq); \
;         ATT_TR(dst[0], va_, 0);     ATT_TR(dst[1], va_, 2048);  ATT_TR(dst[2], va_, 4096);  ATT_TR(dst[3], va_, 6144); \
;         ATT_TR(dst[4], va_, 8192);  ATT_TR(dst[5], va_, 10240); ATT_TR(dst[6], va_, 12288); ATT_TR(dst[7], va_, 14336); } while (0)
; __device__ __forceinline__ void attn_item(CP& P, int L, int sq, int hh, int qt, float lam, float lam_init, LAS unsigned char* lds) {
;     ...
;             ATT_VMM2(va0_, 0, va1_, 1); SB();
;             ATT_VRD(va0_, 2); ATT_VRD(va1_, 3); ATT_LWAIT(); ATT_KRD(t & 3); SB();
	v_pk_add_f32 v[88:89], v[88:89], v[142:143]
	v_mov_b32_e32 v142, 0x60
	s_movk_i32 s1, 0xff60
	v_med3_i32 v142, v158, s1, v142
	v_pk_add_f32 v[80:81], v[80:81], v[150:151]
	v_lshl_add_u32 v150, v142, 2, s0
	v_mov_b32_e32 v142, 0x5f
	s_movk_i32 s1, 0xff5f
	v_med3_i32 v142, v158, s1, v142
	v_lshl_add_u32 v151, v142, 2, s0
	v_mov_b32_e32 v142, 0x5e
	s_movk_i32 s1, 0xff5e
	v_med3_i32 v142, v158, s1, v142
	v_pk_add_f32 v[82:83], v[82:83], v[152:153]
	v_lshl_add_u32 v152, v142, 2, s0
	v_mov_b32_e32 v142, 0x5d
	s_movk_i32 s1, 0xff5d
	v_med3_i32 v142, v158, s1, v142
	v_lshl_add_u32 v153, v142, 2, s0
	v_mov_b32_e32 v142, 0x58
	s_movk_i32 s1, 0xff58
	v_med3_i32 v142, v158, s1, v142
	v_pk_add_f32 v[84:85], v[84:85], v[154:155]
	v_lshl_add_u32 v154, v142, 2, s0
	v_mov_b32_e32 v142, 0x57
	s_movk_i32 s1, 0xff57
	v_med3_i32 v142, v158, s1, v142
	v_lshl_add_u32 v155, v142, 2, s0
	v_mov_b32_e32 v142, 0x56
	s_movk_i32 s1, 0xff56
	v_med3_i32 v142, v158, s1, v142
	v_pk_add_f32 v[86:87], v[86:87], v[156:157]
	v_lshl_add_u32 v156, v142, 2, s0
	v_mov_b32_e32 v142, 0x55
	s_movk_i32 s1, 0xff55
	v_med3_i32 v142, v158, s1, v142
	v_lshl_add_u32 v157, v142, 2, s0
	v_mov_b32_e32 v142, 0x50
	s_movk_i32 s1, 0xff50
	v_med3_i32 v142, v158, s1, v142
	v_mov_b32_e32 v143, 0x4f
	s_movk_i32 s1, 0xff4f
	v_pk_add_f32 v[90:91], v[90:91], v[144:145]
	v_med3_i32 v143, v158, s1, v143
	v_mov_b32_e32 v144, 0x4e
	s_movk_i32 s1, 0xff4e
	v_med3_i32 v144, v158, s1, v144
	s_movk_i32 s1, 0xff4d
	v_med3_i32 v145, v158, s1, v232
	s_movk_i32 s1, 0xff48
	v_pk_add_f32 v[92:93], v[92:93], v[146:147]
	v_med3_i32 v146, v158, s1, v233
	s_movk_i32 s1, 0xff47
	v_med3_i32 v147, v158, s1, v234
	s_movk_i32 s1, 0xff46
	v_pk_add_f32 v[94:95], v[94:95], v[148:149]
	v_med3_i32 v148, v158, s1, v235
	s_movk_i32 s1, 0xff45
	v_med3_i32 v149, v158, s1, v236
	v_lshl_add_u32 v142, v142, 2, s0
	v_lshl_add_u32 v143, v143, 2, s0
	v_lshl_add_u32 v144, v144, 2, s0
	v_lshl_add_u32 v145, v145, 2, s0
	v_lshl_add_u32 v146, v146, 2, s0
	v_lshl_add_u32 v147, v147, 2, s0
	v_lshl_add_u32 v148, v148, 2, s0
	v_lshl_add_u32 v149, v149, 2, s0
	ds_read_b32 v142, v142 offset:704
	ds_read_b32 v143, v143 offset:708
	ds_read_b32 v144, v144 offset:712
	ds_read_b32 v145, v145 offset:716
	ds_read_b32 v146, v146 offset:736
	ds_read_b32 v147, v147 offset:740
	ds_read_b32 v148, v148 offset:744
	ds_read_b32 v149, v149 offset:748
	ds_read_b32 v150, v150 offset:640
	ds_read_b32 v151, v151 offset:644
	ds_read_b32 v152, v152 offset:648
	ds_read_b32 v153, v153 offset:652
	ds_read_b32 v154, v154 offset:672
	ds_read_b32 v155, v155 offset:676
	ds_read_b32 v156, v156 offset:680
	ds_read_b32 v157, v157 offset:684
	s_waitcnt lgkmcnt(0)
	v_pk_add_f32 v[78:79], v[78:79], v[148:149]
	v_pk_add_f32 v[76:77], v[76:77], v[146:147]
	v_pk_add_f32 v[74:75], v[74:75], v[144:145]
	v_pk_add_f32 v[72:73], v[72:73], v[142:143]
	v_pk_add_f32 v[70:71], v[70:71], v[156:157]
	v_pk_add_f32 v[68:69], v[68:69], v[154:155]
	v_pk_add_f32 v[66:67], v[66:67], v[152:153]
	v_pk_add_f32 v[64:65], v[64:65], v[150:151]
	v_mov_b32_e32 v190, 0x7fc00000
.LBB0_74:
	v_mfma_f32_32x32x16_bf16 v[0:15], v[162:165], v[220:223], v[0:15]
	v_max_i32_e32 v142, v80, v64
	v_max3_i32 v142, v142, v81, v65
	v_max3_i32 v142, v142, v82, v66
	v_mfma_f32_32x32x16_bf16 v[48:63], v[178:181], v[220:223], v[48:63]
	v_max3_i32 v142, v142, v83, v67
	v_max3_i32 v142, v142, v84, v68
	v_max3_i32 v142, v142, v85, v69
	v_mfma_f32_32x32x16_bf16 v[0:15], v[166:169], v[216:219], v[0:15]
	v_max3_i32 v142, v142, v86, v70
	v_max3_i32 v142, v142, v87, v71
	v_mfma_f32_32x32x16_bf16 v[48:63], v[182:185], v[216:219], v[48:63]
	v_max3_i32 v142, v142, v88, v72
	v_max3_i32 v142, v142, v89, v73
	v_max3_i32 v142, v142, v90, v74
	v_mfma_f32_32x32x16_bf16 v[0:15], v[170:173], v[212:215], v[0:15]
	v_max3_i32 v142, v142, v91, v75
	v_max3_i32 v142, v142, v92, v76
	v_max3_i32 v142, v142, v93, v77
	v_mfma_f32_32x32x16_bf16 v[48:63], v[186:189], v[212:215], v[48:63]
	v_max3_i32 v142, v142, v94, v78
	v_max3_i32 v142, v142, v95, v79
	v_mfma_f32_32x32x16_bf16 v[0:15], v[174:177], v[208:211], v[0:15]
	v_mov_b32_e32 v143, v142
	s_nop 1
	v_permlane32_swap_b32_e32 v142, v143
	v_mfma_f32_32x32x16_bf16 v[48:63], v[200:203], v[208:211], v[48:63]
	v_max_i32_e32 v142, v142, v143
	s_mov_b32 s0, 0x41000000
	v_cmp_lt_i32_e32 vcc, s0, v142
	v_add_u32_e32 v225, v136, v224
	ds_read_b64_tr_b16 v[162:163], v225 offset:0
	ds_read_b64_tr_b16 v[164:165], v225 offset:2048
	ds_read_b64_tr_b16 v[166:167], v225 offset:4096
	ds_read_b64_tr_b16 v[168:169], v225 offset:6144
	ds_read_b64_tr_b16 v[170:171], v225 offset:8192
	ds_read_b64_tr_b16 v[172:173], v225 offset:10240
	ds_read_b64_tr_b16 v[174:175], v225 offset:12288
	ds_read_b64_tr_b16 v[176:177], v225 offset:14336
	v_add_u32_e32 v224, v135, v224
	ds_read_b64_tr_b16 v[178:179], v224 offset:0
	ds_read_b64_tr_b16 v[180:181], v224 offset:2048
	ds_read_b64_tr_b16 v[182:183], v224 offset:4096
	ds_read_b64_tr_b16 v[184:185], v224 offset:6144
	ds_read_b64_tr_b16 v[186:187], v224 offset:8192
	ds_read_b64_tr_b16 v[188:189], v224 offset:10240
	ds_read_b64_tr_b16 v[200:201], v224 offset:12288
	ds_read_b64_tr_b16 v[202:203], v224 offset:14336
	s_waitcnt lgkmcnt(0)
	s_cbranch_vccz .Latt_fast
	s_setprio 1
	v_mfma_f32_32x32x16_bf16 v[32:47], v[162:165], v[220:223], v[32:47]
	v_mfma_f32_32x32x16_bf16 v[16:31], v[178:181], v[220:223], v[16:31]
	v_mfma_f32_32x32x16_bf16 v[32:47], v[166:169], v[216:219], v[32:47]
	v_mfma_f32_32x32x16_bf16 v[16:31], v[182:185], v[216:219], v[16:31]
	v_mfma_f32_32x32x16_bf16 v[32:47], v[170:173], v[212:215], v[32:47]
	v_mfma_f32_32x32x16_bf16 v[16:31], v[186:189], v[212:215], v[16:31]
	v_mfma_f32_32x32x16_bf16 v[32:47], v[174:177], v[208:211], v[32:47]
	v_mfma_f32_32x32x16_bf16 v[16:31], v[200:203], v[208:211], v[16:31]
	s_setprio 0
	s_nop 15
	v_max_f32_e32 v142, v142, v142
	v_max_f32_e32 v142, 0, v142
	v_exp_f32_e64 v144, -v142
	v_sub_f32_e32 v95, v95, v142
	v_sub_f32_e32 v94, v94, v142
	v_sub_f32_e32 v93, v93, v142
	v_mov_b32_e32 v143, v144
	v_pk_mul_f32 v[14:15], v[14:15], v[144:145] op_sel_hi:[1,0]
	v_pk_mul_f32 v[12:13], v[12:13], v[144:145] op_sel_hi:[1,0]
	v_pk_mul_f32 v[10:11], v[10:11], v[144:145] op_sel_hi:[1,0]
	v_pk_mul_f32 v[8:9], v[8:9], v[144:145] op_sel_hi:[1,0]
	v_pk_mul_f32 v[6:7], v[6:7], v[144:145] op_sel_hi:[1,0]
	v_pk_mul_f32 v[4:5], v[4:5], v[144:145] op_sel_hi:[1,0]
	v_pk_mul_f32 v[2:3], v[2:3], v[144:145] op_sel_hi:[1,0]
	v_pk_mul_f32 v[0:1], v[0:1], v[144:145] op_sel_hi:[1,0]
	v_pk_mul_f32 v[62:63], v[62:63], v[144:145] op_sel_hi:[1,0]
	v_pk_mul_f32 v[60:61], v[60:61], v[144:145] op_sel_hi:[1,0]
	v_pk_mul_f32 v[58:59], v[58:59], v[144:145] op_sel_hi:[1,0]
	v_pk_mul_f32 v[56:57], v[56:57], v[144:145] op_sel_hi:[1,0]
	v_pk_mul_f32 v[54:55], v[54:55], v[144:145] op_sel_hi:[1,0]
	v_pk_mul_f32 v[52:53], v[52:53], v[144:145] op_sel_hi:[1,0]
	v_pk_mul_f32 v[50:51], v[50:51], v[144:145] op_sel_hi:[1,0]
	v_pk_mul_f32 v[48:49], v[48:49], v[144:145] op_sel_hi:[1,0]
	v_pk_mul_f32 v[46:47], v[46:47], v[144:145] op_sel_hi:[1,0]
	v_pk_mul_f32 v[44:45], v[44:45], v[144:145] op_sel_hi:[1,0]
	v_pk_mul_f32 v[42:43], v[42:43], v[144:145] op_sel_hi:[1,0]
	v_pk_mul_f32 v[40:41], v[40:41], v[144:145] op_sel_hi:[1,0]
	v_pk_mul_f32 v[38:39], v[38:39], v[144:145] op_sel_hi:[1,0]
	v_pk_mul_f32 v[36:37], v[36:37], v[144:145] op_sel_hi:[1,0]
	v_pk_mul_f32 v[34:35], v[34:35], v[144:145] op_sel_hi:[1,0]
	v_pk_mul_f32 v[32:33], v[32:33], v[144:145] op_sel_hi:[1,0]
	v_pk_mul_f32 v[30:31], v[30:31], v[144:145] op_sel_hi:[1,0]
	v_pk_mul_f32 v[28:29], v[28:29], v[144:145] op_sel_hi:[1,0]
	v_pk_mul_f32 v[26:27], v[26:27], v[144:145] op_sel_hi:[1,0]
	v_pk_mul_f32 v[24:25], v[24:25], v[144:145] op_sel_hi:[1,0]
	v_pk_mul_f32 v[22:23], v[22:23], v[144:145] op_sel_hi:[1,0]
	v_pk_mul_f32 v[20:21], v[20:21], v[144:145] op_sel_hi:[1,0]
	v_pk_mul_f32 v[18:19], v[18:19], v[144:145] op_sel_hi:[1,0]
	v_pk_mul_f32 v[16:17], v[16:17], v[144:145] op_sel_hi:[1,0]
	v_pk_add_f32 v[144:145], v[124:125], v[142:143]
	v_pk_mul_f32 v[124:125], v[124:125], v[142:143]
	v_sub_f32_e32 v92, v92, v142
	v_mov_b32_e32 v145, v125
	v_sub_f32_e32 v91, v91, v142
	v_sub_f32_e32 v90, v90, v142
	v_sub_f32_e32 v89, v89, v142
	v_sub_f32_e32 v88, v88, v142
	v_sub_f32_e32 v87, v87, v142
	v_sub_f32_e32 v86, v86, v142
	v_sub_f32_e32 v85, v85, v142
	v_sub_f32_e32 v84, v84, v142
	v_sub_f32_e32 v83, v83, v142
	v_sub_f32_e32 v82, v82, v142
	v_sub_f32_e32 v81, v81, v142
	v_sub_f32_e32 v80, v80, v142
	v_sub_f32_e32 v79, v79, v142
	v_sub_f32_e32 v78, v78, v142
	v_sub_f32_e32 v77, v77, v142
	v_sub_f32_e32 v76, v76, v142
	v_sub_f32_e32 v75, v75, v142
	v_sub_f32_e32 v74, v74, v142
	v_sub_f32_e32 v73, v73, v142
	v_sub_f32_e32 v72, v72, v142
	v_sub_f32_e32 v71, v71, v142
	v_sub_f32_e32 v70, v70, v142
	v_sub_f32_e32 v69, v69, v142
	v_sub_f32_e32 v68, v68, v142
	v_sub_f32_e32 v67, v67, v142
	v_sub_f32_e32 v66, v66, v142
	v_sub_f32_e32 v65, v65, v142
	v_sub_f32_e32 v64, v64, v142
	v_mov_b64_e32 v[124:125], v[144:145]
	v_exp_f32_e32 v142, v80
	v_exp_f32_e32 v143, v64
	v_exp_f32_e32 v64, v81
	v_exp_f32_e32 v65, v65
	v_exp_f32_e32 v144, v82
	v_exp_f32_e32 v145, v66
	v_exp_f32_e32 v66, v83
	v_exp_f32_e32 v67, v67
	v_pk_add_f32 v[80:81], v[142:143], 0 op_sel_hi:[1,0]
	v_exp_f32_e32 v82, v84
	v_exp_f32_e32 v83, v68
	v_pk_add_f32 v[80:81], v[64:65], v[80:81]
	v_exp_f32_e32 v68, v85
	v_exp_f32_e32 v69, v69
	v_pk_add_f32 v[80:81], v[144:145], v[80:81]
	v_exp_f32_e32 v84, v86
	v_exp_f32_e32 v85, v70
	v_pk_add_f32 v[80:81], v[66:67], v[80:81]
	v_exp_f32_e32 v86, v87
	v_exp_f32_e32 v87, v71
	v_pk_add_f32 v[70:71], v[82:83], v[80:81]
	v_exp_f32_e32 v242, v88
	v_exp_f32_e32 v243, v72
	v_pk_add_f32 v[70:71], v[68:69], v[70:71]
	v_exp_f32_e32 v88, v89
	v_exp_f32_e32 v89, v73
	v_pk_add_f32 v[70:71], v[84:85], v[70:71]
	v_exp_f32_e32 v246, v90
	v_exp_f32_e32 v247, v74
	v_pk_add_f32 v[70:71], v[86:87], v[70:71]
	v_exp_f32_e32 v90, v91
	v_exp_f32_e32 v91, v75
	v_pk_add_f32 v[70:71], v[242:243], v[70:71]
	v_exp_f32_e32 v248, v92
	v_exp_f32_e32 v249, v76
	v_pk_add_f32 v[70:71], v[88:89], v[70:71]
	v_exp_f32_e32 v92, v93
	v_exp_f32_e32 v93, v77
	v_pk_add_f32 v[70:71], v[246:247], v[70:71]
	v_exp_f32_e32 v250, v94
	v_exp_f32_e32 v251, v78
	v_pk_add_f32 v[70:71], v[90:91], v[70:71]
	v_exp_f32_e32 v94, v95
	v_exp_f32_e32 v95, v79
	v_pk_add_f32 v[70:71], v[248:249], v[70:71]
	s_branch .Latt_tail
; #define ATT_WAITBAR(N) do { asm volatile("s_waitcnt vmcnt(" #N ") lgkmcnt(0)" ::: "memory"); __builtin_amdgcn_s_barrier(); asm volatile("" ::: "memory"); } while (0)
; #define SB() __builtin_amdgcn_sched_barrier(0)
; #define ATT_QKM(t) do { _Pragma("unroll") for (int kb = 0; kb < 2; ++kb) _Pragma("unroll") for (int i = 0; i < 16; ++i) p[kb][i] = cinit_; \
;         SB(); __builtin_amdgcn_s_setprio(1); \
;         _Pragma("unroll") for (int s_ = 0; s_ < 4; ++s_) _Pragma("unroll") for (int kb = 0; kb < 2; ++kb) p[kb] = MFMA32(kf[kb * 4 + s_], qf[s_], p[kb]); \
;         __builtin_amdgcn_s_setprio(0); SB(); } while (0)
; #define ATT_LWAIT() asm volatile("s_waitcnt lgkmcnt(0)" ::: "memory")
; __device__ __forceinline__ void attn_item(CP& P, int L, int sq, int hh, int qt, float lam, float lam_init, LAS unsigned char* lds) {
;     ...
;             ATT_VMM2(va0_, 2, va1_, 3); SB(); ATT_LWAIT(); SB();
;         } else { ATT_KRD(0); ATT_LWAIT(); SB(); }
;         ATT_QKM(t);
;         ATT_SOFTMAX(t);
;         ATT_WAITBAR(4);
.Latt_fast:
	v_mfma_f32_32x32x16_bf16 v[32:47], v[162:165], v[220:223], v[32:47]
	v_exp_f32_e32 v142, v80
	v_exp_f32_e32 v143, v64
	v_exp_f32_e32 v64, v81
	v_exp_f32_e32 v65, v65
	v_exp_f32_e32 v144, v82
	v_exp_f32_e32 v145, v66
	v_mfma_f32_32x32x16_bf16 v[16:31], v[178:181], v[220:223], v[16:31]
	v_exp_f32_e32 v66, v83
	v_exp_f32_e32 v67, v67
	v_pk_add_f32 v[80:81], v[142:143], 0 op_sel_hi:[1,0]
	v_exp_f32_e32 v82, v84
	v_exp_f32_e32 v83, v68
	v_mfma_f32_32x32x16_bf16 v[32:47], v[166:169], v[216:219], v[32:47]
	v_pk_add_f32 v[80:81], v[64:65], v[80:81]
	v_exp_f32_e32 v68, v85
	v_exp_f32_e32 v69, v69
	v_pk_add_f32 v[80:81], v[144:145], v[80:81]
	v_exp_f32_e32 v84, v86
	v_exp_f32_e32 v85, v70
	v_mfma_f32_32x32x16_bf16 v[16:31], v[182:185], v[216:219], v[16:31]
	v_pk_add_f32 v[80:81], v[66:67], v[80:81]
	v_exp_f32_e32 v86, v87
	v_exp_f32_e32 v87, v71
	v_pk_add_f32 v[70:71], v[82:83], v[80:81]
	v_exp_f32_e32 v242, v88
	v_mfma_f32_32x32x16_bf16 v[32:47], v[170:173], v[212:215], v[32:47]
	v_exp_f32_e32 v243, v72
	v_pk_add_f32 v[70:71], v[68:69], v[70:71]
	v_exp_f32_e32 v88, v89
	v_exp_f32_e32 v89, v73
	v_pk_add_f32 v[70:71], v[84:85], v[70:71]
	v_exp_f32_e32 v246, v90
	v_mfma_f32_32x32x16_bf16 v[16:31], v[186:189], v[212:215], v[16:31]
	v_exp_f32_e32 v247, v74
	v_pk_add_f32 v[70:71], v[86:87], v[70:71]
	v_exp_f32_e32 v90, v91
	v_exp_f32_e32 v91, v75
	v_pk_add_f32 v[70:71], v[242:243], v[70:71]
	v_exp_f32_e32 v248, v92
	v_mfma_f32_32x32x16_bf16 v[32:47], v[174:177], v[208:211], v[32:47]
	v_exp_f32_e32 v249, v76
	v_pk_add_f32 v[70:71], v[88:89], v[70:71]
	v_exp_f32_e32 v92, v93
	v_exp_f32_e32 v93, v77
	v_pk_add_f32 v[70:71], v[246:247], v[70:71]
	v_mfma_f32_32x32x16_bf16 v[16:31], v[200:203], v[208:211], v[16:31]
	v_exp_f32_e32 v250, v94
	v_exp_f32_e32 v251, v78
	v_pk_add_f32 v[70:71], v[90:91], v[70:71]
	v_exp_f32_e32 v94, v95
	v_exp_f32_e32 v95, v79
	v_pk_add_f32 v[70:71], v[248:249], v[70:71]
.Latt_tail:
	s_waitcnt vmcnt(4) lgkmcnt(0)
	s_barrier
	v_pk_add_f32 v[70:71], v[92:93], v[70:71]
	v_cvt_pk_bf16_f32 v220, v142, v64
	v_pk_add_f32 v[70:71], v[250:251], v[70:71]
	s_add_i32 s16, s16, 1
	v_pk_add_f32 v[224:225], v[94:95], v[70:71]
	s_add_i32 s20, s20, 0x8000
	v_add_f32_e32 v64, v224, v225
	s_add_i32 s14, s14, 64
	v_cvt_pk_bf16_f32 v221, v144, v66
	v_cvt_pk_bf16_f32 v222, v82, v68
	v_cvt_pk_bf16_f32 v223, v84, v86
	v_cvt_pk_bf16_f32 v216, v242, v88
	v_cvt_pk_bf16_f32 v217, v246, v90
	v_cvt_pk_bf16_f32 v218, v248, v92
	v_cvt_pk_bf16_f32 v219, v250, v94
	v_cvt_pk_bf16_f32 v212, v143, v65
	v_cvt_pk_bf16_f32 v213, v145, v67
	v_cvt_pk_bf16_f32 v214, v83, v69
	v_cvt_pk_bf16_f32 v215, v85, v87
	v_cvt_pk_bf16_f32 v208, v243, v89
	v_cvt_pk_bf16_f32 v209, v247, v91
	v_cvt_pk_bf16_f32 v210, v249, v93
	v_cvt_pk_bf16_f32 v211, v251, v95
	v_add_f32_e32 v125, v125, v64
	s_cmp_eq_u32 s15, s16
	s_cbranch_scc0 .LBB0_67
